# attention epilogue rewritten: output rows stored as 8 dwordx4 per lane via v_permlane32_swap pairs instead of 16 dwordx2; scalar v_mul instead of v_pk_mul
# baseline (speedup 1.0000x reference)
.LBB0_1332:
	ds_read_b128 v[164:167], v144 offset:49152
	ds_read_b128 v[168:171], v144 offset:53248
	ds_read_b128 v[176:179], v144 offset:57344
	ds_read_b128 v[226:229], v144 offset:61440
	ds_read_b128 v[202:205], v145 offset:49152
	ds_read_b128 v[206:209], v145 offset:53248
	ds_read_b128 v[210:213], v145 offset:57344
	ds_read_b128 v[214:217], v145 offset:61440
	v_xor_b32_e32 v84, 32, v193
	v_lshlrev_b32_e32 v84, 2, v84
	ds_bpermute_b32 v88, v84, v200
	s_add_i32 s97, s97, s91
	v_and_or_b32 v90, v191, 31, s97
	v_ashrrev_i32_e32 v91, 31, v90
	v_lshlrev_b64 v[90:91], 11, v[90:91]
	v_lshl_add_u64 v[90:91], s[70:71], 0, v[90:91]
	v_lshrrev_b32_e32 v89, 1, v191
	v_and_b32_e32 v180, 16, v89
	v_lshl_add_u64 v[90:91], v[90:91], 0, v[180:181]
	s_waitcnt lgkmcnt(8)
	v_mfma_f32_32x32x16_bf16 v[48:63], v[164:167], v[68:71], v[48:63]
	s_waitcnt lgkmcnt(7)
	v_mfma_f32_32x32x16_bf16 v[32:47], v[168:171], v[68:71], v[32:47]
	s_waitcnt lgkmcnt(6)
	v_mfma_f32_32x32x16_bf16 v[16:31], v[176:179], v[68:71], v[16:31]
	s_waitcnt lgkmcnt(5)
	v_mfma_f32_32x32x16_bf16 v[0:15], v[226:229], v[68:71], v[0:15]
	s_waitcnt lgkmcnt(4)
	v_mfma_f32_32x32x16_bf16 v[48:63], v[202:205], v[64:67], v[48:63]
	s_waitcnt lgkmcnt(3)
	v_mfma_f32_32x32x16_bf16 v[32:47], v[206:209], v[64:67], v[32:47]
	s_waitcnt lgkmcnt(2)
	v_mfma_f32_32x32x16_bf16 v[16:31], v[210:213], v[64:67], v[16:31]
	s_waitcnt lgkmcnt(1)
	v_mfma_f32_32x32x16_bf16 v[0:15], v[214:217], v[64:67], v[0:15]
	s_waitcnt lgkmcnt(0)
	v_add_f32_e32 v72, v200, v88
	v_div_scale_f32 v73, s[0:1], v72, v72, 1.0
	v_rcp_f32_e32 v74, v73
	s_nop 0
	v_fma_f32 v75, -v73, v74, 1.0
	v_fmac_f32_e32 v74, v75, v74
	v_div_scale_f32 v76, vcc, 1.0, v72, 1.0
	v_mul_f32_e32 v77, v76, v74
	v_fma_f32 v78, -v73, v77, v76
	v_fmac_f32_e32 v77, v78, v74
	v_fma_f32 v76, -v73, v77, v76
	s_nop 3
	v_div_fmas_f32 v79, v76, v74, v77
	v_div_fixup_f32 v79, v79, v72, 1.0
	s_nop 15
	s_nop 3
	v_mul_f32_e32 v48, v48, v79
	v_mul_f32_e32 v49, v49, v79
	v_mul_f32_e32 v50, v50, v79
	v_mul_f32_e32 v51, v51, v79
	v_mul_f32_e32 v52, v52, v79
	v_mul_f32_e32 v53, v53, v79
	v_mul_f32_e32 v54, v54, v79
	v_mul_f32_e32 v55, v55, v79
	v_cvt_pk_bf16_f32 v96, v48, v49
	v_cvt_pk_bf16_f32 v97, v50, v51
	v_cvt_pk_bf16_f32 v98, v52, v53
	v_cvt_pk_bf16_f32 v99, v54, v55
	s_nop 1
	v_permlane32_swap_b32_e32 v96, v98
	v_permlane32_swap_b32_e32 v97, v99
	global_store_dwordx4 v[90:91], v[96:99], off
	v_mul_f32_e32 v56, v56, v79
	v_mul_f32_e32 v57, v57, v79
	v_mul_f32_e32 v58, v58, v79
	v_mul_f32_e32 v59, v59, v79
	v_mul_f32_e32 v60, v60, v79
	v_mul_f32_e32 v61, v61, v79
	v_mul_f32_e32 v62, v62, v79
	v_mul_f32_e32 v63, v63, v79
	v_cvt_pk_bf16_f32 v100, v56, v57
	v_cvt_pk_bf16_f32 v101, v58, v59
	v_cvt_pk_bf16_f32 v102, v60, v61
	v_cvt_pk_bf16_f32 v103, v62, v63
	s_nop 1
	v_permlane32_swap_b32_e32 v100, v102
	v_permlane32_swap_b32_e32 v101, v103
	global_store_dwordx4 v[90:91], v[100:103], off offset:32
	v_mul_f32_e32 v32, v32, v79
	v_mul_f32_e32 v33, v33, v79
	v_mul_f32_e32 v34, v34, v79
	v_mul_f32_e32 v35, v35, v79
	v_mul_f32_e32 v36, v36, v79
	v_mul_f32_e32 v37, v37, v79
	v_mul_f32_e32 v38, v38, v79
	v_mul_f32_e32 v39, v39, v79
	v_cvt_pk_bf16_f32 v104, v32, v33
	v_cvt_pk_bf16_f32 v105, v34, v35
	v_cvt_pk_bf16_f32 v106, v36, v37
	v_cvt_pk_bf16_f32 v107, v38, v39
	s_nop 1
	v_permlane32_swap_b32_e32 v104, v106
	v_permlane32_swap_b32_e32 v105, v107
	global_store_dwordx4 v[90:91], v[104:107], off offset:64
	v_mul_f32_e32 v40, v40, v79
	v_mul_f32_e32 v41, v41, v79
	v_mul_f32_e32 v42, v42, v79
	v_mul_f32_e32 v43, v43, v79
	v_mul_f32_e32 v44, v44, v79
	v_mul_f32_e32 v45, v45, v79
	v_mul_f32_e32 v46, v46, v79
	v_mul_f32_e32 v47, v47, v79
	v_cvt_pk_bf16_f32 v108, v40, v41
	v_cvt_pk_bf16_f32 v109, v42, v43
	v_cvt_pk_bf16_f32 v110, v44, v45
	v_cvt_pk_bf16_f32 v111, v46, v47
	s_nop 1
	v_permlane32_swap_b32_e32 v108, v110
	v_permlane32_swap_b32_e32 v109, v111
	global_store_dwordx4 v[90:91], v[108:111], off offset:96
	v_mul_f32_e32 v16, v16, v79
	v_mul_f32_e32 v17, v17, v79
	v_mul_f32_e32 v18, v18, v79
	v_mul_f32_e32 v19, v19, v79
	v_mul_f32_e32 v20, v20, v79
	v_mul_f32_e32 v21, v21, v79
	v_mul_f32_e32 v22, v22, v79
	v_mul_f32_e32 v23, v23, v79
	v_cvt_pk_bf16_f32 v112, v16, v17
	v_cvt_pk_bf16_f32 v113, v18, v19
	v_cvt_pk_bf16_f32 v114, v20, v21
	v_cvt_pk_bf16_f32 v115, v22, v23
	s_nop 1
	v_permlane32_swap_b32_e32 v112, v114
	v_permlane32_swap_b32_e32 v113, v115
	global_store_dwordx4 v[90:91], v[112:115], off offset:128
	v_mul_f32_e32 v24, v24, v79
	v_mul_f32_e32 v25, v25, v79
	v_mul_f32_e32 v26, v26, v79
	v_mul_f32_e32 v27, v27, v79
	v_mul_f32_e32 v28, v28, v79
	v_mul_f32_e32 v29, v29, v79
	v_mul_f32_e32 v30, v30, v79
	v_mul_f32_e32 v31, v31, v79
	v_cvt_pk_bf16_f32 v116, v24, v25
	v_cvt_pk_bf16_f32 v117, v26, v27
	v_cvt_pk_bf16_f32 v118, v28, v29
	v_cvt_pk_bf16_f32 v119, v30, v31
	s_nop 1
	v_permlane32_swap_b32_e32 v116, v118
	v_permlane32_swap_b32_e32 v117, v119
	global_store_dwordx4 v[90:91], v[116:119], off offset:160
	v_mul_f32_e32 v0, v0, v79
	v_mul_f32_e32 v1, v1, v79
	v_mul_f32_e32 v2, v2, v79
	v_mul_f32_e32 v3, v3, v79
	v_mul_f32_e32 v4, v4, v79
	v_mul_f32_e32 v5, v5, v79
	v_mul_f32_e32 v6, v6, v79
	v_mul_f32_e32 v7, v7, v79
	v_cvt_pk_bf16_f32 v120, v0, v1
	v_cvt_pk_bf16_f32 v121, v2, v3
	v_cvt_pk_bf16_f32 v122, v4, v5
	v_cvt_pk_bf16_f32 v123, v6, v7
	s_nop 1
	v_permlane32_swap_b32_e32 v120, v122
	v_permlane32_swap_b32_e32 v121, v123
	global_store_dwordx4 v[90:91], v[120:123], off offset:192
	v_mul_f32_e32 v8, v8, v79
	v_mul_f32_e32 v9, v9, v79
	v_mul_f32_e32 v10, v10, v79
	v_mul_f32_e32 v11, v11, v79
	v_mul_f32_e32 v12, v12, v79
	v_mul_f32_e32 v13, v13, v79
	v_mul_f32_e32 v14, v14, v79
	v_mul_f32_e32 v15, v15, v79
	v_cvt_pk_bf16_f32 v124, v8, v9
	v_cvt_pk_bf16_f32 v125, v10, v11
	v_cvt_pk_bf16_f32 v126, v12, v13
	v_cvt_pk_bf16_f32 v127, v14, v15
	s_nop 1
	v_permlane32_swap_b32_e32 v124, v126
	v_permlane32_swap_b32_e32 v125, v127
	global_store_dwordx4 v[90:91], v[124:127], off offset:224
	s_add_i32 s96, s96, 1
	s_cmp_eq_u32 s96, 4
	s_barrier
	s_cbranch_scc1 .LBB0_1329
